# l0 retention: gate rows and group-norm gain requested at the start of the unit together with its inputs
# baseline (speedup 1.0000x reference)
.LBB0_1097:
	s_or_b64 exec, exec, s[34:35]
	s_waitcnt lgkmcnt(0)
	s_barrier
	ds_read_b64 v[10:11], v23 offset:280
	v_or_b32_e32 v84, s73, v1
	v_ashrrev_i32_e32 v85, 31, v84
	s_lshl_b32 s42, s36, 2
	s_mov_b32 s67, s43
	s_waitcnt lgkmcnt(0)
	v_readfirstlane_b32 s34, v10
	v_readfirstlane_b32 s35, v11
	v_lshlrev_b64 v[10:11], 13, v[84:85]
	s_add_u32 s37, s34, s42
	v_lshl_add_u64 v[10:11], s[44:45], 0, v[10:11]
	s_addc_u32 s64, s35, 0
	s_lshl_b32 s66, s51, 2
	v_lshl_add_u64 v[10:11], v[10:11], 0, s[42:43]
	v_lshlrev_b32_e32 v30, 2, v98
	v_mov_b32_e32 v31, v23
	v_lshl_add_u64 v[10:11], v[10:11], 0, s[66:67]
	v_lshl_add_u64 v[10:11], v[10:11], 0, v[30:31]
	v_add_co_u32_e64 v10, s[34:35], s72, v10
	v_mov_b64_e32 v[32:33], s[54:55]
	s_nop 0
	v_addc_co_u32_e64 v11, s[34:35], 0, v11, s[34:35]
	s_waitcnt vmcnt(0)
	v_mov_b64_e32 v[80:81], v[226:227]
	v_mov_b64_e32 v[82:83], v[228:229]
	s_add_u32 s34, s37, s66
	s_addc_u32 s35, s64, 0
	v_or_b32_e32 v104, s73, v66
	s_nop 0
	v_mov_b64_e32 v[10:11], v[230:231]
	v_mov_b64_e32 v[12:13], v[232:233]
	ds_read2st64_b32 v[86:87], v65 offset1:1
	ds_read2st64_b32 v[88:89], v65 offset0:2 offset1:3
	ds_read2st64_b32 v[90:91], v65 offset0:4 offset1:5
	ds_read2st64_b32 v[92:93], v65 offset0:6 offset1:7
	ds_read2st64_b32 v[94:95], v67 offset1:1
	ds_read2st64_b32 v[96:97], v67 offset0:2 offset1:3
	ds_read2st64_b32 v[100:101], v67 offset0:4 offset1:5
	ds_read2st64_b32 v[102:103], v67 offset0:6 offset1:7
	s_waitcnt lgkmcnt(7)
	v_mov_b32_e32 v109, v86
	s_waitcnt lgkmcnt(3)
	v_mov_b32_e32 v108, v94
	v_mov_b32_e32 v86, v95
	s_waitcnt lgkmcnt(2)
	v_mov_b32_e32 v94, v96
	v_mov_b32_e32 v95, v88
	v_mov_b32_e32 v88, v97
	s_waitcnt lgkmcnt(1)
	v_mov_b32_e32 v96, v100
	v_mov_b32_e32 v97, v90
	v_mov_b32_e32 v90, v101
	s_waitcnt lgkmcnt(0)
	v_mov_b32_e32 v100, v102
	v_mov_b32_e32 v101, v92
	v_mov_b32_e32 v92, v103
	v_pk_add_f32 v[102:103], v[108:109], 0 op_sel_hi:[1,0]
	v_lshlrev_b64 v[84:85], 11, v[84:85]
	v_pk_add_f32 v[86:87], v[102:103], v[86:87]
	s_mov_b32 s37, s43
	v_pk_add_f32 v[86:87], v[86:87], v[94:95]
	v_ashrrev_i32_e32 v105, 31, v104
	v_pk_add_f32 v[86:87], v[86:87], v[88:89]
	v_lshl_add_u64 v[84:85], s[38:39], 0, v[84:85]
	v_pk_add_f32 v[86:87], v[86:87], v[96:97]
	s_lshl_b32 s36, s36, 1
	v_pk_add_f32 v[86:87], v[86:87], v[90:91]
	s_mov_b32 s65, s43
	v_pk_add_f32 v[86:87], v[86:87], v[100:101]
	v_lshlrev_b64 v[106:107], 13, v[104:105]
	v_pk_add_f32 v[86:87], v[86:87], v[92:93]
	s_lshl_b32 s64, s51, 1
	v_pk_fma_f32 v[86:87], v[86:87], s[52:53], v[32:33] op_sel_hi:[1,0,0]
	v_lshl_add_u64 v[84:85], v[84:85], 0, s[36:37]
	v_mul_f32_e32 v27, 0x4b800000, v87
	v_cmp_gt_f32_e64 s[34:35], s69, v87
	v_lshlrev_b32_e32 v28, 1, v98
	v_mov_b32_e32 v29, v23
	v_cndmask_b32_e64 v27, v87, v27, s[34:35]
	v_rsq_f32_e32 v27, v27
	v_lshl_add_u64 v[106:107], s[44:45], 0, v[106:107]
	v_lshl_add_u64 v[84:85], v[84:85], 0, s[64:65]
	v_lshl_add_u64 v[106:107], v[106:107], 0, s[42:43]
	v_lshl_add_u64 v[84:85], v[84:85], 0, v[28:29]
	v_or_b32_e32 v94, s73, v70
	v_ashrrev_i32_e32 v95, 31, v94
	v_lshlrev_b64 v[96:97], 13, v[94:95]
	v_lshl_add_u64 v[96:97], s[44:45], 0, v[96:97]
	v_lshl_add_u64 v[96:97], v[96:97], 0, s[42:43]
	s_add_i32 s40, s40, s56
	v_lshl_add_u64 v[24:25], v[24:25], 0, s[46:47]
	s_nop 0
	v_mul_f32_e32 v79, 0xbfb8aa3b, v80
	v_mul_f32_e32 v87, 0xbfb8aa3b, v81
	v_mul_f32_e32 v88, 0xbfb8aa3b, v82
	v_mul_f32_e32 v89, 0xbfb8aa3b, v83
	v_exp_f32_e32 v79, v79
	v_exp_f32_e32 v87, v87
	v_exp_f32_e32 v88, v88
	v_exp_f32_e32 v89, v89
	v_add_f32_e32 v79, 1.0, v79
	v_add_f32_e32 v87, 1.0, v87
	v_add_f32_e32 v90, 1.0, v88
	v_add_f32_e32 v91, 1.0, v89
	v_rcp_f32_e32 v88, v79
	v_rcp_f32_e32 v89, v87
	v_rcp_f32_e32 v90, v90
	v_rcp_f32_e32 v91, v91
	v_mul_f32_e32 v79, 0x45800000, v27
	v_pk_mul_f32 v[80:81], v[80:81], v[88:89]
	v_cndmask_b32_e64 v92, v27, v79, s[34:35]
	v_pk_mul_f32 v[82:83], v[82:83], v[90:91]
	v_pk_mul_f32 v[18:19], v[18:19], v[80:81]
	v_pk_mul_f32 v[20:21], v[20:21], v[82:83]
	v_pk_mul_f32 v[18:19], v[92:93], v[18:19] op_sel_hi:[0,1]
	v_pk_mul_f32 v[20:21], v[92:93], v[20:21] op_sel_hi:[0,1]
	s_nop 0
	v_pk_mul_f32 v[18:19], v[10:11], v[18:19]
	v_pk_mul_f32 v[20:21], v[12:13], v[20:21]
	v_cvt_pk_bf16_f32 v18, v18, v19
	v_cvt_pk_bf16_f32 v19, v20, v21
	global_store_dwordx2 v[84:85], v[18:19], off offset:1024
	v_lshl_add_u64 v[18:19], v[106:107], 0, s[66:67]
	v_lshl_add_u64 v[18:19], v[18:19], 0, v[30:31]
	v_add_co_u32_e64 v18, s[34:35], s72, v18
	v_or_b32_e32 v80, s73, v68
	s_nop 0
	v_addc_co_u32_e64 v19, s[34:35], 0, v19, s[34:35]
	v_mov_b64_e32 v[18:19], v[208:209]
	v_mov_b64_e32 v[20:21], v[210:211]
	v_ashrrev_i32_e32 v81, 31, v80
	v_lshlrev_b64 v[84:85], 13, v[80:81]
	v_lshl_add_u64 v[84:85], s[44:45], 0, v[84:85]
	v_lshl_add_u64 v[84:85], v[84:85], 0, s[42:43]
	v_lshl_add_u64 v[84:85], v[84:85], 0, s[66:67]
	v_lshl_add_u64 v[84:85], v[84:85], 0, v[30:31]
	v_add_co_u32_e64 v84, s[34:35], s72, v84
	v_mul_f32_e32 v27, 0x4b800000, v86
	s_nop 0
	v_addc_co_u32_e64 v85, s[34:35], 0, v85, s[34:35]
	v_cmp_gt_f32_e64 s[34:35], s69, v86
	v_lshlrev_b64 v[82:83], 11, v[104:105]
	v_lshl_add_u64 v[82:83], s[38:39], 0, v[82:83]
	v_cndmask_b32_e64 v27, v86, v27, s[34:35]
	v_rsq_f32_e32 v27, v27
	v_lshl_add_u64 v[82:83], v[82:83], 0, s[36:37]
	v_lshl_add_u64 v[82:83], v[82:83], 0, s[64:65]
	v_lshl_add_u64 v[82:83], v[82:83], 0, v[28:29]
	v_lshlrev_b64 v[80:81], 11, v[80:81]
	v_lshl_add_u64 v[80:81], s[38:39], 0, v[80:81]
	s_nop 0
	v_mul_f32_e32 v79, 0xbfb8aa3b, v18
	v_mul_f32_e32 v86, 0xbfb8aa3b, v19
	v_mul_f32_e32 v87, 0xbfb8aa3b, v20
	v_mul_f32_e32 v88, 0xbfb8aa3b, v21
	v_exp_f32_e32 v79, v79
	v_exp_f32_e32 v86, v86
	v_exp_f32_e32 v87, v87
	v_exp_f32_e32 v88, v88
	v_add_f32_e32 v79, 1.0, v79
	v_add_f32_e32 v89, 1.0, v86
	v_add_f32_e32 v90, 1.0, v87
	v_add_f32_e32 v91, 1.0, v88
	v_rcp_f32_e32 v86, v79
	v_rcp_f32_e32 v87, v89
	v_rcp_f32_e32 v88, v90
	v_rcp_f32_e32 v89, v91
	v_mul_f32_e32 v79, 0x45800000, v27
	v_pk_mul_f32 v[18:19], v[18:19], v[86:87]
	v_cndmask_b32_e64 v90, v27, v79, s[34:35]
	v_pk_mul_f32 v[20:21], v[20:21], v[88:89]
	v_pk_mul_f32 v[14:15], v[14:15], v[18:19]
	v_pk_mul_f32 v[16:17], v[16:17], v[20:21]
	v_pk_mul_f32 v[14:15], v[90:91], v[14:15] op_sel_hi:[0,1]
	v_pk_mul_f32 v[16:17], v[90:91], v[16:17] op_sel_hi:[0,1]
	v_pk_mul_f32 v[14:15], v[10:11], v[14:15]
	v_pk_mul_f32 v[16:17], v[12:13], v[16:17]
	v_cvt_pk_bf16_f32 v14, v14, v15
	v_cvt_pk_bf16_f32 v15, v16, v17
	global_store_dwordx2 v[82:83], v[14:15], off offset:1024
	v_mov_b64_e32 v[14:15], v[212:213]
	v_mov_b64_e32 v[16:17], v[214:215]
	ds_read2st64_b32 v[18:19], v69 offset1:1
	ds_read2st64_b32 v[20:21], v69 offset0:2 offset1:3
	ds_read2st64_b32 v[82:83], v69 offset0:4 offset1:5
	ds_read2st64_b32 v[84:85], v69 offset0:6 offset1:7
	ds_read2st64_b32 v[86:87], v71 offset1:1
	ds_read2st64_b32 v[88:89], v71 offset0:2 offset1:3
	ds_read2st64_b32 v[90:91], v71 offset0:4 offset1:5
	ds_read2st64_b32 v[92:93], v71 offset0:6 offset1:7
	s_waitcnt lgkmcnt(7)
	v_mov_b32_e32 v101, v18
	s_waitcnt lgkmcnt(3)
	v_mov_b32_e32 v100, v86
	v_mov_b32_e32 v18, v87
	s_waitcnt lgkmcnt(2)
	v_mov_b32_e32 v86, v88
	v_mov_b32_e32 v87, v20
	v_mov_b32_e32 v20, v89
	s_waitcnt lgkmcnt(1)
	v_mov_b32_e32 v88, v90
	v_mov_b32_e32 v89, v82
	v_mov_b32_e32 v82, v91
	s_waitcnt lgkmcnt(0)
	v_mov_b32_e32 v90, v92
	v_mov_b32_e32 v91, v84
	v_mov_b32_e32 v84, v93
	v_pk_add_f32 v[92:93], v[100:101], 0 op_sel_hi:[1,0]
	s_nop 0
	v_mul_f32_e32 v79, 0xbfb8aa3b, v17
	v_pk_add_f32 v[18:19], v[92:93], v[18:19]
	v_exp_f32_e32 v79, v79
	v_pk_add_f32 v[18:19], v[18:19], v[86:87]
	v_lshl_add_u64 v[86:87], v[96:97], 0, s[66:67]
	v_pk_add_f32 v[18:19], v[18:19], v[20:21]
	v_lshl_add_u64 v[20:21], v[86:87], 0, v[30:31]
	v_pk_add_f32 v[18:19], v[18:19], v[88:89]
	v_add_co_u32_e64 v20, s[34:35], s72, v20
	v_pk_add_f32 v[18:19], v[18:19], v[82:83]
	s_nop 0
	v_addc_co_u32_e64 v21, s[34:35], 0, v21, s[34:35]
	v_pk_add_f32 v[18:19], v[18:19], v[90:91]
	v_lshl_add_u64 v[30:31], v[80:81], 0, s[36:37]
	v_pk_add_f32 v[18:19], v[18:19], v[84:85]
	v_add_f32_e32 v79, 1.0, v79
	v_pk_fma_f32 v[18:19], v[18:19], s[52:53], v[32:33] op_sel_hi:[1,0,0]
	v_mul_f32_e32 v32, 0xbfb8aa3b, v15
	v_mul_f32_e32 v27, 0x4b800000, v19
	v_cmp_gt_f32_e64 s[34:35], s69, v19
	v_mul_f32_e32 v33, 0xbfb8aa3b, v16
	v_exp_f32_e32 v32, v32
	v_cndmask_b32_e64 v19, v19, v27, s[34:35]
	v_mul_f32_e32 v27, 0xbfb8aa3b, v14
	v_exp_f32_e32 v27, v27
	v_exp_f32_e32 v33, v33
	v_add_f32_e32 v80, 1.0, v32
	v_rsq_f32_e32 v19, v19
	v_add_f32_e32 v27, 1.0, v27
	v_add_f32_e32 v81, 1.0, v33
	v_rcp_f32_e32 v32, v27
	v_rcp_f32_e32 v33, v80
	v_rcp_f32_e32 v80, v81
	v_rcp_f32_e32 v81, v79
	v_mul_f32_e32 v27, 0x45800000, v19
	v_pk_mul_f32 v[14:15], v[14:15], v[32:33]
	v_cndmask_b32_e64 v82, v19, v27, s[34:35]
	v_pk_mul_f32 v[16:17], v[16:17], v[80:81]
	v_pk_mul_f32 v[6:7], v[6:7], v[14:15]
	v_pk_mul_f32 v[8:9], v[8:9], v[16:17]
	v_pk_mul_f32 v[6:7], v[82:83], v[6:7] op_sel_hi:[0,1]
	v_pk_mul_f32 v[8:9], v[82:83], v[8:9] op_sel_hi:[0,1]
	v_lshl_add_u64 v[30:31], v[30:31], 0, s[64:65]
	v_pk_mul_f32 v[6:7], v[10:11], v[6:7]
	v_pk_mul_f32 v[8:9], v[12:13], v[8:9]
	v_lshl_add_u64 v[30:31], v[30:31], 0, v[28:29]
	v_cvt_pk_bf16_f32 v6, v6, v7
	v_cvt_pk_bf16_f32 v7, v8, v9
	global_store_dwordx2 v[30:31], v[6:7], off offset:1024
	v_mov_b64_e32 v[6:7], v[216:217]
	v_mov_b64_e32 v[8:9], v[218:219]
	v_mul_f32_e32 v16, 0x4b800000, v18
	v_cmp_gt_f32_e64 s[34:35], s69, v18
	v_lshlrev_b64 v[14:15], 11, v[94:95]
	v_lshl_add_u64 v[14:15], s[38:39], 0, v[14:15]
	v_cndmask_b32_e64 v16, v18, v16, s[34:35]
	v_rsq_f32_e32 v20, v16
	v_lshl_add_u64 v[14:15], v[14:15], 0, s[36:37]
	s_add_i32 s53, s53, s55
	v_lshl_add_u64 v[14:15], v[14:15], 0, s[64:65]
	v_mul_f32_e32 v21, 0x45800000, v20
	v_cndmask_b32_e64 v20, v20, v21, s[34:35]
	s_cmpk_lt_i32 s40, 0x180
	v_lshl_add_u64 v[14:15], v[14:15], 0, v[28:29]
	s_nop 0
	v_mul_f32_e32 v16, 0xbfb8aa3b, v6
	v_mul_f32_e32 v17, 0xbfb8aa3b, v7
	v_mul_f32_e32 v18, 0xbfb8aa3b, v8
	v_mul_f32_e32 v19, 0xbfb8aa3b, v9
	v_exp_f32_e32 v16, v16
	v_exp_f32_e32 v17, v17
	v_exp_f32_e32 v18, v18
	v_exp_f32_e32 v19, v19
	v_add_f32_e32 v16, 1.0, v16
	v_add_f32_e32 v17, 1.0, v17
	v_add_f32_e32 v18, 1.0, v18
	v_add_f32_e32 v19, 1.0, v19
	v_rcp_f32_e32 v16, v16
	v_rcp_f32_e32 v17, v17
	v_rcp_f32_e32 v18, v18
	v_rcp_f32_e32 v19, v19
	v_pk_mul_f32 v[6:7], v[6:7], v[16:17]
	s_nop 0
	v_pk_mul_f32 v[2:3], v[2:3], v[6:7]
	v_pk_mul_f32 v[8:9], v[8:9], v[18:19]
	v_pk_mul_f32 v[2:3], v[20:21], v[2:3] op_sel_hi:[0,1]
	v_pk_mul_f32 v[4:5], v[4:5], v[8:9]
	v_pk_mul_f32 v[2:3], v[10:11], v[2:3]
	v_pk_mul_f32 v[4:5], v[20:21], v[4:5] op_sel_hi:[0,1]
	v_pk_mul_f32 v[4:5], v[12:13], v[4:5]
	v_cvt_pk_bf16_f32 v2, v2, v3
	v_cvt_pk_bf16_f32 v3, v4, v5
	global_store_dwordx2 v[14:15], v[2:3], off offset:1024
	s_barrier
	s_cbranch_scc0 .LBB0_1106
.LBB0_1098:
	ds_read_b64 v[2:3], v23 offset:272
	s_cmpk_lt_i32 s40, 0x100
	s_cselect_b32 s34, s41, 0x7fffffc0
	s_and_b32 s64, s40, 3
	s_lshl_b32 s36, s64, 2
	s_and_b32 s73, s34, s53
	s_waitcnt lgkmcnt(0)
	v_readfirstlane_b32 s34, v2
	v_readfirstlane_b32 s35, v3
	v_mov_b32_e32 v2, s36
	s_nop 3
	global_load_dword v79, v2, s[34:35]
	global_load_dword v124, v2, s[34:35] offset:16
	v_or_b32_e32 v2, s73, v99
	v_ashrrev_i32_e32 v3, 31, v2
	v_lshlrev_b64 v[2:3], 13, v[2:3]
	v_lshl_add_u64 v[18:19], s[44:45], 0, v[2:3]
	s_lshl_b32 s42, s64, 8
	v_lshl_add_u64 v[2:3], v[18:19], 0, s[42:43]
	v_lshl_add_u64 v[14:15], v[2:3], 0, v[22:23]
	global_load_dwordx4 v[2:5], v[14:15], off offset:1664
	global_load_dwordx4 v[6:9], v[14:15], off offset:1680
	global_load_dwordx4 v[10:13], v[14:15], off offset:2688
	s_nop 0
	global_load_dwordx4 v[14:17], v[14:15], off offset:2704
	s_lshl_b32 s42, s64, 9
	v_lshl_add_u64 v[18:19], v[18:19], 0, s[42:43]
	v_mov_b32_e32 v27, v23
	v_lshl_add_u64 v[32:33], v[18:19], 0, v[26:27]
	global_load_dwordx4 v[18:21], v[32:33], off offset:3712
	global_load_dwordx4 v[28:31], v[32:33], off offset:3728
	v_add_co_u32_e64 v100, s[34:35], s57, v24
	v_lshl_add_u64 v[96:97], v[24:25], 0, s[48:49]
	s_nop 0
	v_addc_co_u32_e64 v101, s[34:35], -1, v25, s[34:35]
	global_load_dwordx4 v[80:83], v[24:25], off
	global_load_dwordx4 v[84:87], v[24:25], off offset:-16
	global_load_dwordx4 v[88:91], v[24:25], off offset:-32
	global_load_dwordx4 v[92:95], v[24:25], off offset:-48
	s_nop 0
	global_load_dwordx4 v[100:103], v[100:101], off offset:-48
	s_nop 0
	global_load_dwordx4 v[104:107], v[96:97], off offset:48
	global_load_dwordx4 v[108:111], v[96:97], off offset:32
	global_load_dwordx4 v[112:115], v[96:97], off offset:16
	global_load_dwordx4 v[116:119], v[32:33], off offset:3760
	global_load_dwordx4 v[120:123], v[32:33], off offset:3744
	ds_read_b64 v[220:221], v23 offset:280
	v_or_b32_e32 v222, s73, v1
	v_ashrrev_i32_e32 v223, 31, v222
	v_lshlrev_b64 v[222:223], 13, v[222:223]
	v_lshl_add_u64 v[222:223], s[44:45], 0, v[222:223]
	s_lshl_b32 s98, s64, 9
	s_lshl_b32 s100, s51, 2
	s_add_u32 s98, s98, s100
	s_mov_b32 s99, 0
	v_lshl_add_u64 v[222:223], v[222:223], 0, s[98:99]
	v_lshlrev_b32_e32 v224, 2, v98
	v_mov_b32_e32 v225, 0
	v_lshl_add_u64 v[222:223], v[222:223], 0, v[224:225]
	s_mov_b64 s[100:101], 0x1000
	v_lshl_add_u64 v[222:223], v[222:223], 0, s[100:101]
	s_mov_b64 s[100:101], 0x20000
	v_lshl_add_u64 v[200:201], v[222:223], 0, s[100:101]
	v_lshl_add_u64 v[202:203], v[200:201], 0, s[100:101]
	v_lshl_add_u64 v[204:205], v[202:203], 0, s[100:101]
	global_load_dwordx4 v[226:229], v[222:223], off offset:1664
	global_load_dwordx4 v[208:211], v[200:201], off offset:1664
	global_load_dwordx4 v[212:215], v[202:203], off offset:1664
	global_load_dwordx4 v[216:219], v[204:205], off offset:1664
	s_waitcnt lgkmcnt(0)
	v_readfirstlane_b32 s100, v220
	v_readfirstlane_b32 s101, v221
	s_nop 1
	s_add_u32 s100, s100, s98
	s_addc_u32 s101, s101, 0
	global_load_dwordx4 v[230:233], v224, s[100:101]
	s_waitcnt vmcnt(22)
	v_mul_f32_e32 v27, 0xbfb8aa3b, v79
	s_waitcnt vmcnt(21)
	v_mul_f32_e32 v32, 0xbfb8aa3b, v124
	v_exp_f32_e32 v27, v27
	v_exp_f32_e32 v32, v32
	s_waitcnt vmcnt(20)
	v_cvt_pk_bf16_f32 v124, v2, v3
	v_cvt_pk_bf16_f32 v125, v4, v5
	s_waitcnt vmcnt(18)
	v_pk_mul_f32 v[10:11], v[10:11], s[50:51] op_sel_hi:[1,0]
	v_pk_mul_f32 v[12:13], v[12:13], s[50:51] op_sel_hi:[1,0]
	s_waitcnt vmcnt(17)
	v_pk_mul_f32 v[16:17], v[16:17], s[50:51] op_sel_hi:[1,0]
	v_pk_mul_f32 v[14:15], v[14:15], s[50:51] op_sel_hi:[1,0]
	v_cvt_pk_bf16_f32 v10, v10, v11
	v_cvt_pk_bf16_f32 v11, v12, v13
	v_cvt_pk_bf16_f32 v13, v16, v17
	v_add_f32_e32 v17, 1.0, v27
	v_cvt_pk_bf16_f32 v12, v14, v15
	s_waitcnt vmcnt(16)
	v_cvt_pk_bf16_f32 v14, v18, v19
	v_rcp_f32_e32 v18, v17
	v_add_f32_e32 v17, 1.0, v32
	v_rcp_f32_e32 v19, v17
	v_cvt_pk_bf16_f32 v15, v20, v21
	v_cmp_gt_f32_e64 s[34:35], s69, v18
	ds_write_b128 v72, v[10:13] offset:9216
	v_cmp_gt_f32_e64 s[36:37], s69, v19
	v_cndmask_b32_e64 v20, 0, v78, s[34:35]
	s_and_b64 s[34:35], s[34:35], exec
	s_cselect_b32 s42, 32, 0
	s_and_b64 s[34:35], s[36:37], exec
	v_ldexp_f32 v18, v18, s42
	s_cselect_b32 s34, 32, 0
	v_log_f32_e32 v18, v18
	v_ldexp_f32 v19, v19, s34
	v_log_f32_e32 v19, v19
	v_cndmask_b32_e64 v21, 0, v78, s[36:37]
	v_mul_f32_e32 v10, 0x3f317217, v18
	v_fma_f32 v10, v18, s70, -v10
	v_mul_f32_e32 v11, 0x3f317217, v19
	v_fmac_f32_e32 v10, 0x3377d1cf, v18
	v_fma_f32 v11, v19, s70, -v11
	v_fmac_f32_e32 v10, 0x3f317217, v18
	v_fmac_f32_e32 v11, 0x3377d1cf, v19
	v_cmp_lt_f32_e64 s[34:35], |v18|, s71
	v_fmac_f32_e32 v11, 0x3f317217, v19
	v_cvt_pk_bf16_f32 v126, v6, v7
	v_cndmask_b32_e64 v10, v18, v10, s[34:35]
	v_cmp_lt_f32_e64 s[34:35], |v19|, s71
	v_sub_f32_e32 v27, v10, v20
	v_cvt_pk_bf16_f32 v127, v8, v9
	v_cndmask_b32_e64 v10, v19, v11, s[34:35]
	v_sub_f32_e32 v32, v10, v21
	v_mul_f32_e32 v10, v27, v34
	v_mul_f32_e32 v11, v32, v35
	v_mul_f32_e32 v10, 0x3fb8aa3b, v10
	v_mul_f32_e32 v11, 0x3fb8aa3b, v11
	v_exp_f32_e32 v10, v10
	v_exp_f32_e32 v18, v11
	s_waitcnt vmcnt(15)
	v_cvt_pk_bf16_f32 v16, v28, v29
	v_cvt_pk_bf16_f32 v17, v30, v31
	v_pk_mul_f32 v[12:13], v[2:3], v[10:11] op_sel_hi:[1,0]
	v_pk_mul_f32 v[20:21], v[4:5], v[10:11] op_sel_hi:[1,0]
	v_pk_mul_f32 v[28:29], v[6:7], v[10:11] op_sel_hi:[1,0]
	v_pk_mul_f32 v[30:31], v[8:9], v[10:11] op_sel_hi:[1,0]
	v_pk_mul_f32 v[2:3], v[2:3], v[18:19] op_sel_hi:[1,0]
	v_pk_mul_f32 v[4:5], v[4:5], v[18:19] op_sel_hi:[1,0]
	v_pk_mul_f32 v[6:7], v[6:7], v[18:19] op_sel_hi:[1,0]
	v_pk_mul_f32 v[8:9], v[8:9], v[18:19] op_sel_hi:[1,0]
	v_cvt_pk_bf16_f32 v10, v12, v13
	v_cvt_pk_bf16_f32 v11, v20, v21
	v_cvt_pk_bf16_f32 v12, v28, v29
	v_cvt_pk_bf16_f32 v13, v30, v31
	v_cvt_pk_bf16_f32 v2, v2, v3
	v_cvt_pk_bf16_f32 v3, v4, v5
	v_cvt_pk_bf16_f32 v4, v6, v7
	v_cvt_pk_bf16_f32 v5, v8, v9
	ds_write_b128 v72, v[124:127] offset:1024
	ds_write_b128 v72, v[10:13] offset:17408
	ds_write_b128 v72, v[2:5] offset:25600
	ds_write_b128 v73, v[14:17] offset:41984
	s_waitcnt vmcnt(10)
	v_cvt_pk_bf16_f32 v2, v100, v101
	v_cvt_pk_bf16_f32 v3, v102, v103
	s_waitcnt vmcnt(7)
	v_cvt_pk_bf16_f32 v4, v112, v113
	v_cvt_pk_bf16_f32 v5, v114, v115
	ds_write_b128 v73, v[2:5] offset:60416
	v_cvt_pk_bf16_f32 v2, v92, v93
	v_cvt_pk_bf16_f32 v3, v94, v95
	v_cvt_pk_bf16_f32 v4, v88, v89
	v_cvt_pk_bf16_f32 v5, v90, v91
	v_add_u32_e32 v6, 0x13400, v73
	ds_write_b128 v6, v[2:5]
	s_waitcnt vmcnt(5)
	v_cvt_pk_bf16_f32 v2, v120, v121
	v_cvt_pk_bf16_f32 v3, v122, v123
	v_cvt_pk_bf16_f32 v4, v116, v117
	v_cvt_pk_bf16_f32 v5, v118, v119
	ds_write_b128 v73, v[2:5] offset:42000
	v_cvt_pk_bf16_f32 v2, v108, v109
	v_cvt_pk_bf16_f32 v3, v110, v111
	v_cvt_pk_bf16_f32 v4, v104, v105
	v_cvt_pk_bf16_f32 v5, v106, v107
	ds_write_b128 v73, v[2:5] offset:60432
	v_cvt_pk_bf16_f32 v2, v84, v85
	v_cvt_pk_bf16_f32 v3, v86, v87
	v_cvt_pk_bf16_f32 v4, v80, v81
	v_cvt_pk_bf16_f32 v5, v82, v83
	ds_write_b128 v6, v[2:5] offset:16
	v_add_u32_e32 v2, v39, v42
	s_waitcnt lgkmcnt(0)
	s_barrier
	ds_read_b128 v[2:5], v2 offset:9216
	v_add_u32_e32 v6, v39, v43
	v_add_u32_e32 v10, v45, v42
	ds_read_b128 v[6:9], v6 offset:9216
	ds_read_b128 v[10:13], v10 offset:1024
	v_add_u32_e32 v14, v45, v43
	ds_read_b128 v[14:17], v14 offset:1024
	s_waitcnt lgkmcnt(1)
	v_mfma_f32_16x16x32_bf16 v[10:13], v[2:5], v[10:13], 0
	s_waitcnt lgkmcnt(0)
	v_mfma_f32_16x16x32_bf16 v[10:13], v[6:9], v[14:17], v[10:13]
	v_mul_f32_e32 v15, v32, v47
	v_mul_f32_e32 v15, 0x3fb8aa3b, v15
	v_mul_f32_e32 v14, v27, v46
	v_exp_f32_e32 v17, v15
	v_mul_f32_e32 v15, v27, v48
	v_mul_f32_e32 v14, 0x3fb8aa3b, v14
	v_mul_f32_e32 v15, 0x3fb8aa3b, v15
	v_exp_f32_e32 v14, v14
	v_exp_f32_e32 v15, v15
	v_mul_f32_e32 v16, v32, v49
	v_mul_f32_e32 v16, 0x3fb8aa3b, v16
	v_exp_f32_e32 v16, v16
	v_pk_add_f32 v[14:15], v[14:15], 0 op_sel_hi:[1,0]
	s_nop 0
	v_cndmask_b32_e64 v19, v14, 0, vcc
	v_cndmask_b32_e64 v18, 0, v15, s[4:5]
	v_pk_add_f32 v[16:17], v[16:17], v[18:19]
	s_nop 0
	v_cndmask_b32_e64 v15, v16, v15, s[6:7]
	v_cndmask_b32_e64 v14, v17, v14, s[4:5]
	v_pk_mul_f32 v[10:11], v[14:15], v[10:11]
	v_mul_f32_e32 v15, v32, v51
	v_mul_f32_e32 v15, 0x3fb8aa3b, v15
	v_mul_f32_e32 v14, v27, v50
	v_exp_f32_e32 v16, v15
	v_mul_f32_e32 v15, v27, v52
	v_mul_f32_e32 v14, 0x3fb8aa3b, v14
	v_mul_f32_e32 v15, 0x3fb8aa3b, v15
	v_exp_f32_e32 v14, v14
	v_exp_f32_e32 v15, v15
	v_mul_f32_e32 v17, v32, v53
	v_mul_f32_e32 v17, 0x3fb8aa3b, v17
	v_exp_f32_e32 v17, v17
	v_pk_add_f32 v[14:15], v[14:15], 0 op_sel_hi:[1,0]
	s_nop 0
	v_cndmask_b32_e64 v19, v15, 0, s[8:9]
	v_cndmask_b32_e64 v18, v14, 0, s[10:11]
	v_pk_add_f32 v[16:17], v[16:17], v[18:19]
	s_nop 0
	v_cndmask_b32_e64 v15, v17, v15, s[12:13]
	v_cndmask_b32_e64 v14, v16, v14, s[14:15]
	v_pk_mul_f32 v[12:13], v[14:15], v[12:13]
	v_cvt_pk_bf16_f32 v14, v10, v11
	v_add_u32_e32 v10, v55, v42
	v_cvt_pk_bf16_f32 v15, v12, v13
	ds_read_b128 v[10:13], v10 offset:1024
	v_add_u32_e32 v16, v38, v44
	ds_write_b64 v16, v[14:15] offset:33792
	v_add_u32_e32 v14, v55, v43
	ds_read_b128 v[14:17], v14 offset:1024
	s_waitcnt lgkmcnt(2)
	v_mfma_f32_16x16x32_bf16 v[2:5], v[2:5], v[10:13], 0
	v_mul_f32_e32 v10, v27, v56
	v_mul_f32_e32 v10, 0x3fb8aa3b, v10
	v_exp_f32_e32 v10, v10
	v_mul_f32_e32 v11, v32, v57
	v_mul_f32_e32 v11, 0x3fb8aa3b, v11
	v_exp_f32_e32 v11, v11
	s_waitcnt lgkmcnt(0)
	v_mfma_f32_16x16x32_bf16 v[2:5], v[6:9], v[14:17], v[2:5]
	v_add_f32_e32 v6, 0, v10
	v_cndmask_b32_e64 v7, v6, 0, s[16:17]
	v_add_f32_e32 v7, v11, v7
	v_cndmask_b32_e64 v6, v7, v6, s[18:19]
	v_mul_f32_e32 v7, v27, v58
	v_mul_f32_e32 v7, 0x3fb8aa3b, v7
	v_exp_f32_e32 v7, v7
	v_mul_f32_e32 v8, v32, v59
	v_mul_f32_e32 v8, 0x3fb8aa3b, v8
	v_exp_f32_e32 v8, v8
	v_mul_f32_e32 v10, v6, v2
	v_add_f32_e32 v2, 0, v7
	v_cndmask_b32_e64 v6, 0, v2, s[18:19]
	v_add_f32_e32 v6, v8, v6
	v_cndmask_b32_e64 v2, v6, v2, s[20:21]
	v_mul_f32_e32 v11, v2, v3
	v_mul_f32_e32 v3, v32, v61
	v_mul_f32_e32 v3, 0x3fb8aa3b, v3
	v_mul_f32_e32 v2, v27, v60
	v_exp_f32_e32 v6, v3
	v_mul_f32_e32 v3, v27, v62
	v_mul_f32_e32 v2, 0x3fb8aa3b, v2
	v_mul_f32_e32 v3, 0x3fb8aa3b, v3
	v_exp_f32_e32 v2, v2
	v_exp_f32_e32 v3, v3
	v_mul_f32_e32 v7, v32, v63
	v_mul_f32_e32 v7, 0x3fb8aa3b, v7
	v_exp_f32_e32 v7, v7
	v_pk_add_f32 v[2:3], v[2:3], 0 op_sel_hi:[1,0]
	s_nop 0
	v_cndmask_b32_e64 v9, v3, 0, s[22:23]
	v_cndmask_b32_e64 v8, v2, 0, s[24:25]
	v_pk_add_f32 v[6:7], v[6:7], v[8:9]
	s_nop 0
	v_cndmask_b32_e64 v3, v7, v3, s[26:27]
	v_cndmask_b32_e64 v2, v6, v2, s[28:29]
	v_pk_mul_f32 v[2:3], v[2:3], v[4:5]
	v_cvt_pk_bf16_f32 v4, v10, v11
	v_cvt_pk_bf16_f32 v5, v2, v3
	v_add_u32_e32 v2, v38, v54
	v_add_u32_e32 v6, v37, v64
	ds_write_b64 v2, v[4:5] offset:33792
	s_waitcnt lgkmcnt(0)
	s_barrier
	ds_read_b64_tr_b16 v[2:3], v6 offset:41984
	ds_read_b64_tr_b16 v[4:5], v6 offset:43136
	ds_read_b64_tr_b16 v[10:11], v6 offset:51200
	ds_read_b64_tr_b16 v[12:13], v6 offset:52352
	ds_read_b64_tr_b16 v[28:29], v6 offset:60416
	ds_read_b64_tr_b16 v[30:31], v6 offset:61568
	ds_read_b128 v[6:9], v76 offset:33792
	ds_read_b64_tr_b16 v[80:81], v75
	ds_read_b64_tr_b16 v[82:83], v75 offset:1152
	ds_read_b128 v[14:17], v76 offset:17408
	ds_read_b128 v[84:87], v76 offset:35840
	s_waitcnt lgkmcnt(4)
	v_mfma_f32_16x16x32_bf16 v[6:9], v[2:5], v[6:9], 0
	ds_read_b64_tr_b16 v[88:89], v74 offset:60416
	ds_read_b64_tr_b16 v[90:91], v74 offset:61568
	ds_read_b128 v[18:21], v76 offset:25600
	ds_read_b128 v[92:95], v76 offset:19456
	s_waitcnt lgkmcnt(5)
	v_mfma_f32_16x16x32_bf16 v[6:9], v[28:31], v[14:17], v[6:9]
	ds_read_b64_tr_b16 v[100:101], v75 offset:9216
	ds_read_b64_tr_b16 v[102:103], v75 offset:10368
	ds_read_b128 v[14:17], v76 offset:27648
	s_waitcnt lgkmcnt(4)
	v_mfma_f32_16x16x32_bf16 v[6:9], v[80:83], v[18:21], v[6:9]
	ds_read_b128 v[18:21], v77 offset:33792
	ds_read_b128 v[104:107], v77 offset:35840
	s_waitcnt lgkmcnt(1)
	v_mfma_f32_16x16x32_bf16 v[6:9], v[10:13], v[18:21], v[6:9]
	ds_read_b128 v[18:21], v77 offset:17408
	ds_read_b128 v[108:111], v77 offset:19456
	s_waitcnt lgkmcnt(1)
	v_mfma_f32_16x16x32_bf16 v[6:9], v[88:91], v[18:21], v[6:9]
	ds_read_b128 v[18:21], v77 offset:25600
	ds_read_b128 v[112:115], v77 offset:27648
	s_waitcnt lgkmcnt(1)
	v_mfma_f32_16x16x32_bf16 v[18:21], v[100:103], v[18:21], v[6:9]
	v_mfma_f32_16x16x32_bf16 v[6:9], v[2:5], v[84:87], 0
	v_mfma_f32_16x16x32_bf16 v[6:9], v[28:31], v[92:95], v[6:9]
	v_mfma_f32_16x16x32_bf16 v[6:9], v[80:83], v[14:17], v[6:9]
	v_mfma_f32_16x16x32_bf16 v[6:9], v[10:13], v[104:107], v[6:9]
	v_mfma_f32_16x16x32_bf16 v[6:9], v[88:91], v[108:111], v[6:9]
	s_waitcnt lgkmcnt(0)
	v_mfma_f32_16x16x32_bf16 v[14:17], v[100:103], v[112:115], v[6:9]
	s_nop 5
	ds_read_b128 v[6:9], v76 offset:37888
	ds_read_b128 v[84:87], v76 offset:39936
	ds_read_b128 v[92:95], v76 offset:21504
	ds_read_b128 v[104:107], v76 offset:23552
	s_waitcnt lgkmcnt(3)
	v_mfma_f32_16x16x32_bf16 v[6:9], v[2:5], v[6:9], 0
	s_waitcnt lgkmcnt(2)
	v_mfma_f32_16x16x32_bf16 v[2:5], v[2:5], v[84:87], 0
	s_waitcnt lgkmcnt(1)
	v_mfma_f32_16x16x32_bf16 v[6:9], v[28:31], v[92:95], v[6:9]
	ds_read_b128 v[92:95], v76 offset:29696
	ds_read_b128 v[108:111], v76 offset:31744
	s_waitcnt lgkmcnt(2)
	v_mfma_f32_16x16x32_bf16 v[2:5], v[28:31], v[104:107], v[2:5]
	s_waitcnt lgkmcnt(1)
	v_mfma_f32_16x16x32_bf16 v[6:9], v[80:83], v[92:95], v[6:9]
	ds_read_b128 v[92:95], v77 offset:37888
	ds_read_b128 v[112:115], v77 offset:39936
	s_waitcnt lgkmcnt(2)
	v_mfma_f32_16x16x32_bf16 v[2:5], v[80:83], v[108:111], v[2:5]
	s_waitcnt lgkmcnt(1)
	v_mfma_f32_16x16x32_bf16 v[6:9], v[10:13], v[92:95], v[6:9]
	ds_read_b128 v[92:95], v77 offset:21504
	ds_read_b128 v[116:119], v77 offset:23552
	s_waitcnt lgkmcnt(2)
	v_mfma_f32_16x16x32_bf16 v[2:5], v[10:13], v[112:115], v[2:5]
	v_mul_f32_e32 v10, v19, v19
	v_fmac_f32_e32 v10, v18, v18
	v_fmac_f32_e32 v10, v20, v20
	v_fmac_f32_e32 v10, v21, v21
	ds_bpermute_b32 v11, v40, v10
	s_waitcnt lgkmcnt(2)
	v_mfma_f32_16x16x32_bf16 v[6:9], v[88:91], v[92:95], v[6:9]
	ds_read_b128 v[92:95], v77 offset:29696
	ds_read_b128 v[120:123], v77 offset:31744
	s_waitcnt lgkmcnt(2)
	v_add_f32_e32 v10, v10, v11
	v_mfma_f32_16x16x32_bf16 v[2:5], v[88:91], v[116:119], v[2:5]
	ds_bpermute_b32 v11, v41, v10
	s_waitcnt lgkmcnt(2)
	v_mfma_f32_16x16x32_bf16 v[6:9], v[100:103], v[92:95], v[6:9]
	s_waitcnt lgkmcnt(1)
	v_mfma_f32_16x16x32_bf16 v[2:5], v[100:103], v[120:123], v[2:5]
	s_and_saveexec_b64 s[34:35], s[2:3]
	s_cbranch_execz .LBB0_1100
	s_waitcnt lgkmcnt(0)
	v_add_f32_e32 v10, v10, v11
	ds_write_b32 v36, v10
